# lru_pass1 prompt: the 16 conditional xin loads kept in flight, single wait + shifts at the join block
# baseline (speedup 1.0000x reference)
.LBB0_181:
	s_mul_i32 s2, s12, 0x1200
	s_add_u32 s2, s28, s2
	s_addc_u32 s3, s29, 0
	v_lshl_add_u64 v[4:5], v[0:1], 1, s[2:3]
	v_add_co_u32_e32 v14, vcc, 0x1000, v4
	global_load_ushort v17, v[4:5], off offset:2560
	s_nop 0
	v_addc_co_u32_e32 v15, vcc, 0, v5, vcc
	global_load_ushort v18, v[14:15], off offset:3072
	v_add_co_u32_e32 v14, vcc, 0x2000, v4
	s_cmp_lt_u32 s10, 64
	s_nop 0
	v_addc_co_u32_e32 v15, vcc, 0, v5, vcc
	global_load_ushort v20, v[14:15], off offset:3584
	v_add_co_u32_e32 v14, vcc, 0x4000, v4
	s_cselect_b64 s[8:9], -1, 0
	s_nop 0
	v_addc_co_u32_e32 v15, vcc, 0, v5, vcc
	global_load_ushort v22, v[14:15], off
	v_add_co_u32_e32 v14, vcc, 0x5000, v4
	s_cmp_gt_u32 s10, 63
	s_nop 0
	v_addc_co_u32_e32 v15, vcc, 0, v5, vcc
	global_load_ushort v24, v[14:15], off offset:512
	v_add_co_u32_e32 v14, vcc, 0x6000, v4
	s_nop 1
	v_addc_co_u32_e32 v15, vcc, 0, v5, vcc
	global_load_ushort v26, v[14:15], off offset:1024
	v_add_co_u32_e32 v14, vcc, 0x7000, v4
	s_nop 1
	v_addc_co_u32_e32 v15, vcc, 0, v5, vcc
	global_load_ushort v27, v[14:15], off offset:1536
	v_add_co_u32_e32 v14, vcc, 0x8000, v4
	s_nop 1
	v_addc_co_u32_e32 v15, vcc, 0, v5, vcc
	global_load_ushort v31, v[14:15], off offset:2048
	v_add_co_u32_e32 v14, vcc, 0x9000, v4
	s_nop 1
	v_addc_co_u32_e32 v15, vcc, 0, v5, vcc
	global_load_ushort v33, v[14:15], off offset:2560
	v_add_co_u32_e32 v14, vcc, 0xa000, v4
	s_nop 1
	v_addc_co_u32_e32 v15, vcc, 0, v5, vcc
	global_load_ushort v34, v[14:15], off offset:3072
	v_add_co_u32_e32 v14, vcc, 0xb000, v4
	s_nop 1
	v_addc_co_u32_e32 v15, vcc, 0, v5, vcc
	global_load_ushort v36, v[14:15], off offset:3584
	v_add_co_u32_e32 v14, vcc, 0xd000, v4
	s_nop 1
	v_addc_co_u32_e32 v15, vcc, 0, v5, vcc
	global_load_ushort v37, v[14:15], off
	v_add_co_u32_e32 v14, vcc, 0xe000, v4
	s_nop 1
	v_addc_co_u32_e32 v15, vcc, 0, v5, vcc
	global_load_ushort v40, v[14:15], off offset:512
	v_add_co_u32_e32 v14, vcc, 0xf000, v4
	s_nop 1
	v_addc_co_u32_e32 v15, vcc, 0, v5, vcc
	global_load_ushort v41, v[14:15], off offset:1024
	v_add_co_u32_e32 v14, vcc, 0x10000, v4
	s_nop 1
	v_addc_co_u32_e32 v15, vcc, 0, v5, vcc
	global_load_ushort v42, v[14:15], off offset:1536
	v_add_co_u32_e32 v14, vcc, 0x11000, v4
	s_nop 1
	v_addc_co_u32_e32 v15, vcc, 0, v5, vcc
	global_load_ushort v45, v[14:15], off offset:2048
	v_mov_b32_e32 v14, 0
	v_mov_b32_e32 v15, 0
	s_cbranch_scc1 .LBB0_197
	v_add_co_u32_e32 v28, vcc, 0x12000, v4
	s_nop 1
	v_addc_co_u32_e32 v29, vcc, 0, v5, vcc
	global_load_ushort v15, v[28:29], off offset:2560
	v_cndmask_b32_e64 v16, 0, 1, s[8:9]
	v_cmp_ne_u32_e64 s[10:11], 1, v16
	s_andn2_b64 vcc, exec, s[8:9]
	s_cbranch_vccz .LBB0_198

.LBB0_184:
	v_add_co_u32_e32 v28, vcc, 0x14000, v4
	s_nop 1
	v_addc_co_u32_e32 v29, vcc, 0, v5, vcc
	global_load_ushort v19, v[28:29], off offset:3584
	s_and_b64 vcc, exec, s[10:11]
	s_cbranch_vccz .LBB0_200

.LBB0_186:
	v_add_co_u32_e32 v28, vcc, 0x17000, v4
	s_nop 1
	v_addc_co_u32_e32 v29, vcc, 0, v5, vcc
	global_load_ushort v23, v[28:29], off offset:512
	s_and_b64 vcc, exec, s[10:11]
	s_cbranch_vccz .LBB0_202

.LBB0_188:
	v_add_co_u32_e32 v28, vcc, 0x19000, v4
	s_nop 1
	v_addc_co_u32_e32 v29, vcc, 0, v5, vcc
	global_load_ushort v28, v[28:29], off offset:1536
	s_and_b64 vcc, exec, s[10:11]
	s_cbranch_vccz .LBB0_204

.LBB0_190:
	v_add_co_u32_e32 v38, vcc, 0x1b000, v4
	s_nop 1
	v_addc_co_u32_e32 v39, vcc, 0, v5, vcc
	global_load_ushort v30, v[38:39], off offset:2560
	s_and_b64 vcc, exec, s[10:11]
	s_cbranch_vccz .LBB0_206

.LBB0_192:
	v_add_co_u32_e32 v38, vcc, 0x1d000, v4
	s_nop 1
	v_addc_co_u32_e32 v39, vcc, 0, v5, vcc
	global_load_ushort v35, v[38:39], off offset:3584
	s_and_b64 vcc, exec, s[10:11]
	s_cbranch_vccz .LBB0_208

.LBB0_194:
	v_add_co_u32_e32 v46, vcc, 0x20000, v4
	s_nop 1
	v_addc_co_u32_e32 v47, vcc, 0, v5, vcc
	global_load_ushort v38, v[46:47], off offset:512
	s_and_b64 vcc, exec, s[10:11]
	s_cbranch_vccz .LBB0_210

.LBB0_196:
	v_add_co_u32_e32 v46, vcc, 0x22000, v4
	s_nop 1
	v_addc_co_u32_e32 v47, vcc, 0, v5, vcc
	global_load_ushort v44, v[46:47], off offset:1536
	s_and_b64 vcc, exec, s[10:11]
	s_cbranch_vccz .LBB0_212
	s_branch .LBB0_213

.LBB0_198:
	v_add_co_u32_e32 v28, vcc, 0x13000, v4
	s_nop 1
	v_addc_co_u32_e32 v29, vcc, 0, v5, vcc
	global_load_ushort v14, v[28:29], off offset:3072
	v_mov_b32_e32 v16, 0
	s_and_b64 vcc, exec, s[10:11]
	v_mov_b32_e32 v19, 0
	s_cbranch_vccz .LBB0_184

.LBB0_200:
	v_add_co_u32_e32 v28, vcc, 0x16000, v4
	s_nop 1
	v_addc_co_u32_e32 v29, vcc, 0, v5, vcc
	global_load_ushort v16, v[28:29], off
	v_mov_b32_e32 v21, 0
	s_and_b64 vcc, exec, s[10:11]
	v_mov_b32_e32 v23, 0
	s_cbranch_vccz .LBB0_186

.LBB0_202:
	v_add_co_u32_e32 v28, vcc, 0x18000, v4
	s_nop 1
	v_addc_co_u32_e32 v29, vcc, 0, v5, vcc
	global_load_ushort v21, v[28:29], off offset:1024
	v_mov_b32_e32 v25, 0
	s_and_b64 vcc, exec, s[10:11]
	v_mov_b32_e32 v28, 0
	s_cbranch_vccz .LBB0_188

.LBB0_204:
	v_add_co_u32_e32 v38, vcc, 0x1a000, v4
	s_nop 1
	v_addc_co_u32_e32 v39, vcc, 0, v5, vcc
	global_load_ushort v25, v[38:39], off offset:2048
	v_mov_b32_e32 v29, 0
	s_and_b64 vcc, exec, s[10:11]
	v_mov_b32_e32 v30, 0
	s_cbranch_vccz .LBB0_190

.LBB0_206:
	v_add_co_u32_e32 v38, vcc, 0x1c000, v4
	s_nop 1
	v_addc_co_u32_e32 v39, vcc, 0, v5, vcc
	global_load_ushort v29, v[38:39], off offset:3072
	v_mov_b32_e32 v32, 0
	s_and_b64 vcc, exec, s[10:11]
	v_mov_b32_e32 v35, 0
	s_cbranch_vccz .LBB0_192

.LBB0_208:
	v_add_co_u32_e32 v38, vcc, 0x1f000, v4
	s_nop 1
	v_addc_co_u32_e32 v39, vcc, 0, v5, vcc
	global_load_ushort v32, v[38:39], off
	v_mov_b32_e32 v39, 0
	s_and_b64 vcc, exec, s[10:11]
	v_mov_b32_e32 v38, 0
	s_cbranch_vccz .LBB0_194

.LBB0_210:
	v_add_co_u32_e32 v46, vcc, 0x21000, v4
	s_nop 1
	v_addc_co_u32_e32 v47, vcc, 0, v5, vcc
	global_load_ushort v39, v[46:47], off offset:1024
	v_mov_b32_e32 v43, 0
	s_and_b64 vcc, exec, s[10:11]
	v_mov_b32_e32 v44, 0
	s_cbranch_vccz .LBB0_196

.LBB0_212:
	v_add_co_u32_e32 v4, vcc, 0x23000, v4
	s_nop 1
	v_addc_co_u32_e32 v5, vcc, 0, v5, vcc
	global_load_ushort v43, v[4:5], off offset:2048
.LBB0_213:
	s_waitcnt vmcnt(0)
	v_lshlrev_b32_e32 v15, 16, v15
	v_lshlrev_b32_e32 v19, 16, v19
	v_lshlrev_b32_e32 v23, 16, v23
	v_lshlrev_b32_e32 v28, 16, v28
	v_lshlrev_b32_e32 v30, 16, v30
	v_lshlrev_b32_e32 v35, 16, v35
	v_lshlrev_b32_e32 v38, 16, v38
	v_lshlrev_b32_e32 v44, 16, v44
	v_lshlrev_b32_e32 v14, 16, v14
	v_lshlrev_b32_e32 v16, 16, v16
	v_lshlrev_b32_e32 v21, 16, v21
	v_lshlrev_b32_e32 v25, 16, v25
	v_lshlrev_b32_e32 v29, 16, v29
	v_lshlrev_b32_e32 v32, 16, v32
	v_lshlrev_b32_e32 v39, 16, v39
	v_lshlrev_b32_e32 v43, 16, v43
	s_waitcnt vmcnt(14)
	v_lshlrev_b32_e32 v5, 16, v18
	s_waitcnt vmcnt(12)
	v_lshlrev_b32_e32 v18, 16, v22
	s_waitcnt vmcnt(10)
	v_lshlrev_b32_e32 v22, 16, v26
	s_waitcnt vmcnt(8)
	v_lshlrev_b32_e32 v26, 16, v31
	s_waitcnt vmcnt(6)
	v_lshlrev_b32_e32 v31, 16, v34
	s_waitcnt vmcnt(4)
	v_lshlrev_b32_e32 v34, 16, v37
	s_waitcnt vmcnt(2)
	v_lshlrev_b32_e32 v37, 16, v41
	s_waitcnt vmcnt(1)
	v_lshlrev_b32_e32 v41, 16, v42
	s_waitcnt vmcnt(0)
	v_lshlrev_b32_e32 v42, 16, v45
	v_mul_f32_e32 v45, v9, v11
	v_fmac_f32_e32 v45, v7, v12
	v_lshlrev_b32_e32 v4, 16, v17
	v_fmac_f32_e32 v45, v8, v13
	v_fmac_f32_e32 v45, v6, v4
	v_add_f32_e32 v12, v10, v45
	v_mul_f32_e32 v45, v9, v13
	v_fmac_f32_e32 v45, v7, v11
	v_fmac_f32_e32 v45, v8, v4
	v_fmac_f32_e32 v45, v6, v5
	v_lshlrev_b32_e32 v17, 16, v20
	v_lshlrev_b32_e32 v20, 16, v24
	v_lshlrev_b32_e32 v24, 16, v27
	v_lshlrev_b32_e32 v27, 16, v33
	v_lshlrev_b32_e32 v33, 16, v36
	v_lshlrev_b32_e32 v36, 16, v40
	v_lshlrev_b32_e32 v40, 2, v0
	v_add_f32_e32 v11, v10, v45
	ds_write2st64_b32 v40, v12, v11 offset1:4
	v_mul_f32_e32 v11, v9, v4
	v_mul_f32_e32 v12, v9, v5
	v_fmac_f32_e32 v11, v7, v13
	v_fmac_f32_e32 v12, v7, v4
	v_fmac_f32_e32 v11, v8, v5
	v_fmac_f32_e32 v12, v8, v17
	v_fmac_f32_e32 v11, v6, v17
	v_fmac_f32_e32 v12, v6, v18
	v_add_f32_e32 v11, v10, v11
	v_add_f32_e32 v4, v10, v12
	ds_write2st64_b32 v40, v11, v4 offset0:8 offset1:12
	v_mul_f32_e32 v4, v9, v17
	v_fmac_f32_e32 v4, v7, v5
	v_mul_f32_e32 v5, v9, v18
	v_fmac_f32_e32 v5, v7, v17
	v_fmac_f32_e32 v4, v8, v18
	v_fmac_f32_e32 v5, v8, v20
	v_fmac_f32_e32 v4, v6, v20
	v_fmac_f32_e32 v5, v6, v22
	v_add_f32_e32 v4, v10, v4
	v_add_f32_e32 v5, v10, v5
	ds_write2st64_b32 v40, v4, v5 offset0:16 offset1:20
	v_mul_f32_e32 v4, v9, v20
	v_mul_f32_e32 v5, v9, v22
	v_fmac_f32_e32 v4, v7, v18
	v_fmac_f32_e32 v5, v7, v20
	v_fmac_f32_e32 v4, v8, v22
	v_fmac_f32_e32 v5, v8, v24
	v_fmac_f32_e32 v4, v6, v24
	v_fmac_f32_e32 v5, v6, v26
	v_add_f32_e32 v4, v10, v4
	v_add_f32_e32 v5, v10, v5
	ds_write2st64_b32 v40, v4, v5 offset0:24 offset1:28
	v_mul_f32_e32 v4, v9, v24
	v_mul_f32_e32 v5, v9, v26
	v_fmac_f32_e32 v4, v7, v22
	v_fmac_f32_e32 v5, v7, v24
	v_fmac_f32_e32 v4, v8, v26
	v_fmac_f32_e32 v5, v8, v27
	v_fmac_f32_e32 v4, v6, v27
	v_fmac_f32_e32 v5, v6, v31
	v_add_f32_e32 v4, v10, v4
	v_add_f32_e32 v5, v10, v5
	ds_write2st64_b32 v40, v4, v5 offset0:32 offset1:36
	v_mul_f32_e32 v4, v9, v27
	v_mul_f32_e32 v5, v9, v31
	v_fmac_f32_e32 v4, v7, v26
	v_fmac_f32_e32 v5, v7, v27
	v_fmac_f32_e32 v4, v8, v31
	v_fmac_f32_e32 v5, v8, v33
	v_fmac_f32_e32 v4, v6, v33
	v_fmac_f32_e32 v5, v6, v34
	v_add_f32_e32 v4, v10, v4
	v_add_f32_e32 v5, v10, v5
	ds_write2st64_b32 v40, v4, v5 offset0:40 offset1:44
	v_mul_f32_e32 v4, v9, v33
	v_mul_f32_e32 v5, v9, v34
	v_fmac_f32_e32 v4, v7, v31
	v_fmac_f32_e32 v5, v7, v33
	v_fmac_f32_e32 v4, v8, v34
	v_fmac_f32_e32 v5, v8, v36
	v_fmac_f32_e32 v4, v6, v36
	v_fmac_f32_e32 v5, v6, v37
	v_add_f32_e32 v4, v10, v4
	v_add_f32_e32 v5, v10, v5
	ds_write2st64_b32 v40, v4, v5 offset0:48 offset1:52
	v_mul_f32_e32 v4, v9, v36
	v_mul_f32_e32 v5, v9, v37
	v_fmac_f32_e32 v4, v7, v34
	v_fmac_f32_e32 v5, v7, v36
	v_fmac_f32_e32 v4, v8, v37
	v_fmac_f32_e32 v5, v8, v41
	v_fmac_f32_e32 v4, v6, v41
	v_fmac_f32_e32 v5, v6, v42
	v_add_f32_e32 v4, v10, v4
	v_add_f32_e32 v5, v10, v5
	ds_write2st64_b32 v40, v4, v5 offset0:56 offset1:60
	v_mul_f32_e32 v4, v9, v41
	v_mul_f32_e32 v5, v9, v42
	v_fmac_f32_e32 v4, v7, v37
	v_fmac_f32_e32 v5, v7, v41
	v_fmac_f32_e32 v4, v8, v42
	v_fmac_f32_e32 v5, v8, v15
	v_fmac_f32_e32 v4, v6, v15
	v_fmac_f32_e32 v5, v6, v14
	v_add_f32_e32 v4, v10, v4
	v_add_f32_e32 v5, v10, v5
	v_cndmask_b32_e64 v4, 0, v4, s[8:9]
	v_cndmask_b32_e64 v5, 0, v5, s[8:9]
	ds_write2st64_b32 v40, v4, v5 offset0:64 offset1:68
	v_mul_f32_e32 v4, v9, v15
	v_mul_f32_e32 v5, v9, v14
	v_fmac_f32_e32 v4, v7, v42
	v_fmac_f32_e32 v5, v7, v15
	v_fmac_f32_e32 v4, v8, v14
	v_fmac_f32_e32 v5, v8, v19
	v_fmac_f32_e32 v4, v6, v19
	v_fmac_f32_e32 v5, v6, v16
	v_add_f32_e32 v4, v10, v4
	v_add_f32_e32 v5, v10, v5
	v_cndmask_b32_e64 v4, 0, v4, s[8:9]
	v_cndmask_b32_e64 v5, 0, v5, s[8:9]
	ds_write2st64_b32 v40, v4, v5 offset0:72 offset1:76
	v_mul_f32_e32 v4, v9, v19
	v_mul_f32_e32 v5, v9, v16
	v_fmac_f32_e32 v4, v7, v14
	v_fmac_f32_e32 v5, v7, v19
	v_fmac_f32_e32 v4, v8, v16
	v_fmac_f32_e32 v5, v8, v23
	v_fmac_f32_e32 v4, v6, v23
	v_fmac_f32_e32 v5, v6, v21
	v_add_f32_e32 v4, v10, v4
	v_add_f32_e32 v5, v10, v5
	v_cndmask_b32_e64 v4, 0, v4, s[8:9]
	v_cndmask_b32_e64 v5, 0, v5, s[8:9]
	ds_write2st64_b32 v40, v4, v5 offset0:80 offset1:84
	v_mul_f32_e32 v4, v9, v23
	v_mul_f32_e32 v5, v9, v21
	v_fmac_f32_e32 v4, v7, v16
	v_fmac_f32_e32 v5, v7, v23
	v_fmac_f32_e32 v4, v8, v21
	v_fmac_f32_e32 v5, v8, v28
	v_fmac_f32_e32 v4, v6, v28
	v_fmac_f32_e32 v5, v6, v25
	v_add_f32_e32 v4, v10, v4
	v_add_f32_e32 v5, v10, v5
	v_cndmask_b32_e64 v4, 0, v4, s[8:9]
	v_cndmask_b32_e64 v5, 0, v5, s[8:9]
	ds_write2st64_b32 v40, v4, v5 offset0:88 offset1:92
	v_mul_f32_e32 v4, v9, v28
	v_mul_f32_e32 v5, v9, v25
	v_fmac_f32_e32 v4, v7, v21
	v_fmac_f32_e32 v5, v7, v28
	v_fmac_f32_e32 v4, v8, v25
	v_fmac_f32_e32 v5, v8, v30
	v_fmac_f32_e32 v4, v6, v30
	v_fmac_f32_e32 v5, v6, v29
	v_add_f32_e32 v4, v10, v4
	v_add_f32_e32 v5, v10, v5
	v_cndmask_b32_e64 v4, 0, v4, s[8:9]
	v_cndmask_b32_e64 v5, 0, v5, s[8:9]
	ds_write2st64_b32 v40, v4, v5 offset0:96 offset1:100
	v_mul_f32_e32 v4, v9, v30
	v_mul_f32_e32 v5, v9, v29
	v_fmac_f32_e32 v4, v7, v25
	v_fmac_f32_e32 v5, v7, v30
	v_fmac_f32_e32 v4, v8, v29
	v_fmac_f32_e32 v5, v8, v35
	v_fmac_f32_e32 v4, v6, v35
	v_fmac_f32_e32 v5, v6, v32
	v_add_f32_e32 v4, v10, v4
	v_add_f32_e32 v5, v10, v5
	v_cndmask_b32_e64 v4, 0, v4, s[8:9]
	v_cndmask_b32_e64 v5, 0, v5, s[8:9]
	ds_write2st64_b32 v40, v4, v5 offset0:104 offset1:108
	v_mul_f32_e32 v4, v9, v35
	v_mul_f32_e32 v5, v9, v32
	v_fmac_f32_e32 v4, v7, v29
	v_fmac_f32_e32 v5, v7, v35
	v_fmac_f32_e32 v4, v8, v32
	v_fmac_f32_e32 v5, v8, v38
	v_fmac_f32_e32 v4, v6, v38
	v_fmac_f32_e32 v5, v6, v39
	v_add_f32_e32 v4, v10, v4
	v_add_f32_e32 v5, v10, v5
	v_cndmask_b32_e64 v4, 0, v4, s[8:9]
	v_cndmask_b32_e64 v5, 0, v5, s[8:9]
	ds_write2st64_b32 v40, v4, v5 offset0:112 offset1:116
	v_mul_f32_e32 v4, v9, v38
	v_mul_f32_e32 v5, v9, v39
	v_fmac_f32_e32 v4, v7, v32
	v_fmac_f32_e32 v5, v7, v38
	v_fmac_f32_e32 v4, v8, v39
	v_fmac_f32_e32 v5, v8, v44
	v_fmac_f32_e32 v4, v6, v44
	v_fmac_f32_e32 v5, v6, v43
	v_add_f32_e32 v4, v10, v4
	v_add_f32_e32 v5, v10, v5
	v_readlane_b32 s76, v252, 48
	v_cndmask_b32_e64 v4, 0, v4, s[8:9]
	v_cndmask_b32_e64 v5, 0, v5, s[8:9]
	v_lshlrev_b64 v[2:3], 2, v[2:3]
	v_readlane_b32 s82, v252, 54
	v_readlane_b32 s83, v252, 55
	ds_write2st64_b32 v40, v4, v5 offset0:120 offset1:124
	s_waitcnt lgkmcnt(0)
	v_lshl_add_u64 v[4:5], s[82:83], 0, v[2:3]
	s_barrier
	global_load_dword v6, v[4:5], off
	v_readlane_b32 s77, v252, 49
	v_readlane_b32 s80, v252, 52
	v_readlane_b32 s81, v252, 53
	v_lshl_add_u64 v[4:5], s[76:77], 0, v[2:3]
	global_load_dword v41, v[4:5], off
	v_lshl_add_u64 v[2:3], s[80:81], 0, v[2:3]
	global_load_dword v42, v[2:3], off
	s_mov_b32 s9, 0xbfb8aa3b
	s_sub_i32 s2, 0x810, s5
	v_readfirstlane_b32 s8, v0
	s_min_u32 s10, s2, 32
	s_lshl_b32 s2, s92, 2
	s_ashr_i32 s3, s8, 6
	s_add_i32 s2, s3, s2
	s_ashr_i32 s3, s2, 31
	s_and_b32 s8, s8, 0x3fffffc0
	s_lshl_b64 s[2:3], s[2:3], 14
	v_readlane_b32 s52, v252, 32
	v_readlane_b32 s78, v252, 50
	v_readlane_b32 s79, v252, 51
	s_lshl_b32 s11, s8, 2
	s_add_i32 s8, s10, -1
	v_readlane_b32 s66, v252, 46
	v_readlane_b32 s67, v252, 47
	s_mov_b32 s15, 0
	s_lshr_b32 s13, s8, 4
	s_mov_b32 s14, 0
	v_readlane_b32 s84, v252, 56
	v_readlane_b32 s85, v252, 57
	v_readlane_b32 s86, v252, 58
	v_readlane_b32 s87, v252, 59
	v_readlane_b32 s88, v252, 60
	v_readlane_b32 s89, v252, 61
	v_readlane_b32 s90, v252, 62
	v_readlane_b32 s91, v252, 63
	v_readlane_b32 s53, v252, 33
	v_readlane_b32 s54, v252, 34
	v_readlane_b32 s55, v252, 35
	v_readlane_b32 s56, v252, 36
	v_readlane_b32 s57, v252, 37
	v_readlane_b32 s58, v252, 38
	v_readlane_b32 s59, v252, 39
	v_readlane_b32 s60, v252, 40
	v_readlane_b32 s61, v252, 41
	v_readlane_b32 s62, v252, 42
	v_readlane_b32 s63, v252, 43
	v_readlane_b32 s64, v252, 44
	v_readlane_b32 s65, v252, 45
	s_waitcnt vmcnt(2)
	v_mul_f32_e64 v4, |v6|, s9
	v_exp_f32_e32 v4, v4
	v_max_f32_e64 v2, -v6, -v6
	v_max_f32_e32 v5, 0, v2
	s_mov_b32 s9, 0x3f2aaaab
	v_add_f32_e32 v6, 1.0, v4
	v_add_f32_e32 v2, -1.0, v6
	v_sub_f32_e32 v3, v2, v6
	v_add_f32_e32 v3, 1.0, v3
	v_sub_f32_e32 v2, v4, v2
	v_add_f32_e32 v7, v2, v3
	v_frexp_mant_f32_e32 v8, v6
	v_cvt_f64_f32_e32 v[2:3], v6
	v_frexp_exp_i32_f64_e32 v2, v[2:3]
	v_cmp_gt_f32_e32 vcc, s9, v8
	s_mov_b32 s9, 0x3f317218
	s_nop 0
	v_subbrev_co_u32_e32 v2, vcc, 0, v2, vcc
	v_sub_u32_e32 v3, 0, v2
	v_ldexp_f32 v6, v6, v3
	v_ldexp_f32 v3, v7, v3
	v_add_f32_e32 v7, -1.0, v6
	v_add_f32_e32 v10, 1.0, v6
	v_add_f32_e32 v8, 1.0, v7
	v_add_f32_e32 v11, -1.0, v10
	v_sub_f32_e32 v8, v6, v8
	v_sub_f32_e32 v6, v6, v11
	v_add_f32_e32 v8, v3, v8
	v_add_f32_e32 v3, v3, v6
	v_add_f32_e32 v6, v10, v3
	v_rcp_f32_e32 v11, v6
	v_add_f32_e32 v9, v7, v8
	v_sub_f32_e32 v7, v9, v7
	v_sub_f32_e32 v7, v8, v7
	v_sub_f32_e32 v8, v6, v10
	v_sub_f32_e32 v3, v3, v8
	v_mul_f32_e32 v8, v9, v11
	v_mul_f32_e32 v10, v6, v8
	v_fma_f32 v12, v8, v6, -v10
	v_fmac_f32_e32 v12, v8, v3
	v_add_f32_e32 v13, v10, v12
	v_sub_f32_e32 v14, v9, v13
	v_sub_f32_e32 v9, v9, v14
	v_sub_f32_e32 v10, v13, v10
	v_sub_f32_e32 v9, v9, v13
	v_add_f32_e32 v7, v7, v9
	v_sub_f32_e32 v9, v10, v12
	v_add_f32_e32 v7, v9, v7
	v_add_f32_e32 v9, v14, v7
	v_mul_f32_e32 v10, v11, v9
	v_mul_f32_e32 v12, v6, v10
	v_fma_f32 v6, v10, v6, -v12
	v_fmac_f32_e32 v6, v10, v3
	v_sub_f32_e32 v3, v14, v9
	v_add_f32_e32 v3, v7, v3
	v_add_f32_e32 v7, v12, v6
	v_sub_f32_e32 v13, v9, v7
	v_sub_f32_e32 v9, v9, v13
	v_sub_f32_e32 v12, v7, v12
	v_sub_f32_e32 v7, v9, v7
	v_add_f32_e32 v3, v3, v7
	v_sub_f32_e32 v6, v12, v6
	v_cvt_f32_i32_e32 v2, v2
	v_add_f32_e32 v3, v6, v3
	v_add_f32_e32 v6, v8, v10
	v_add_f32_e32 v3, v13, v3
	v_sub_f32_e32 v7, v6, v8
	v_mul_f32_e32 v3, v11, v3
	v_sub_f32_e32 v7, v10, v7
	v_add_f32_e32 v3, v7, v3
	v_mul_f32_e32 v10, 0x3f317218, v2
	v_add_f32_e32 v7, v6, v3
	v_fma_f32 v11, v2, s9, -v10
	v_mul_f32_e32 v8, v7, v7
	v_fmac_f32_e32 v11, 0xb102e308, v2
	v_sub_f32_e32 v2, v7, v6
	v_fmamk_f32 v9, v8, 0x3e9b6dac, v229
	v_sub_f32_e32 v2, v3, v2
	v_add_f32_e32 v3, v10, v11
	v_fmaak_f32 v9, v8, v9, 0x3f2aaada
	v_sub_f32_e32 v6, v3, v10
	v_ldexp_f32 v10, v7, 1
	v_mul_f32_e32 v7, v7, v8
	v_mul_f32_e32 v7, v7, v9
	v_add_f32_e32 v8, v10, v7
	v_sub_f32_e32 v9, v8, v10
	v_ldexp_f32 v2, v2, 1
	v_sub_f32_e32 v7, v7, v9
	v_add_f32_e32 v2, v2, v7
	v_add_f32_e32 v7, v8, v2
	v_sub_f32_e32 v8, v7, v8
	v_sub_f32_e32 v2, v2, v8
	v_add_f32_e32 v8, v3, v7
	v_sub_f32_e32 v9, v8, v3
	v_sub_f32_e32 v10, v8, v9
	v_sub_f32_e32 v6, v11, v6
	v_sub_f32_e32 v3, v3, v10
	v_sub_f32_e32 v7, v7, v9
	v_add_f32_e32 v3, v7, v3
	v_add_f32_e32 v7, v6, v2
	v_sub_f32_e32 v9, v7, v6
	v_sub_f32_e32 v10, v7, v9
	v_sub_f32_e32 v6, v6, v10
	v_sub_f32_e32 v2, v2, v9
	v_add_f32_e32 v3, v7, v3
	v_add_f32_e32 v2, v2, v6
	v_add_f32_e32 v6, v8, v3
	v_sub_f32_e32 v7, v6, v8
	v_sub_f32_e32 v3, v3, v7
	v_add_f32_e32 v2, v2, v3
	s_mov_b32 s9, 0x7f800000
	v_add_f32_e32 v2, v6, v2
	v_cmp_neq_f32_e32 vcc, s9, v4
	s_mov_b32 s9, 0x33800000
	s_nop 0
	v_cndmask_b32_e32 v2, v233, v2, vcc
	v_cmp_ngt_f32_e32 vcc, -1.0, v4
	s_nop 1
	v_cndmask_b32_e32 v2, v236, v2, vcc
	v_cmp_neq_f32_e32 vcc, -1.0, v4
	s_nop 1
	v_cndmask_b32_e32 v2, v237, v2, vcc
	v_cmp_lt_f32_e64 vcc, |v4|, s9
	s_nop 1
	v_cndmask_b32_e32 v2, v2, v4, vcc
	v_add_f32_e32 v43, v5, v2
	v_and_b32_e32 v2, 63, v0
	v_lshl_or_b32 v4, v2, 2, s2
	v_mov_b32_e32 v5, s3
	v_lshl_add_u64 v[2:3], s[66:67], 0, v[4:5]
	v_lshl_add_u64 v[4:5], s[78:79], 0, v[4:5]
	s_branch .LBB0_215
